# FFT stage 2: cross-unit software pipelining of the tile loads (next unit loads issued after the LDS-write barrier, counted vmcnt at loop top)
# baseline (speedup 1.0000x reference)
; __device__ __forceinline__ int otid(int wv) { int t; asm volatile("v_mbcnt_lo_u32_b32 %0, -1, 0\n\tv_mbcnt_hi_u32_b32 %0, -1, %0\n\tv_lshl_add_u32 %0, %1, 6, %0" : "=&v"(t) : "s"(wv)); return t; }
; __device__ void fft2_phase(int wv, const Params& p, unsigned char* lds) {
;     const int tid = otid(wv), lane = tid & 63, w = __builtin_amdgcn_readfirstlane(tid >> 6), lr = lane & 15, lq = lane >> 4;
;     constexpr int PW = 136;
;     const bf16_t* A1 = (const bf16_t*)(p.ws + WS_BIG2); bf16_t* Y = (bf16_t*)(p.ws + WS_BIG1);
;     const bf16_t* ctg = (const bf16_t*)(p.ws + WS_TAB + TAB_CT128); const bf16_t* stg = (const bf16_t*)(p.ws + WS_TAB + TAB_ST128);
;     bf16_t* CT = (bf16_t*)lds; bf16_t* ST = CT + 128 * PW; bf16_t* XR = ST + 128 * PW; bf16_t* XI = XR + 128 * PW;
;     for (int idx = tid; idx < 128 * 16; idx += NTHR) { const int r = idx >> 4, c8 = (idx & 15) * 8;
;         *(bf16x8*)(CT + r * PW + c8) = *(const bf16x8*)(ctg + r * 128 + c8); *(bf16x8*)(ST + r * PW + c8) = *(const bf16x8*)(stg + r * 128 + c8); }
;     __syncthreads();
;     for (int unit = blockIdx.x; unit < 2048; unit += gridDim.x) {
;         const int gi = unit >> 3, cb = unit & 7;
;         const int seq = gi < 64 ? 0 : (gi < 128 ? 1 : 2); const int ka = gi - (seq == 0 ? 0 : (seq == 1 ? 64 : 128)); const int N1 = seq == 2 ? 128 : 64;
;         const size_t sbase = (size_t)seq * 8192;
; #pragma unroll
;         for (int ps = 0; ps < 4; ++ps) { const int idx = tid + ps * NTHR, b = idx & 127, c8 = (idx >> 7) * 8;
;             const bf16_t* rp = A1 + ((size_t)gi * 128 + b) * 2048 + cb * 128 + c8; const bf16x8 vr = *(const bf16x8*)rp, vi = *(const bf16x8*)(rp + 1024);
; #pragma unroll
;             for (int e = 0; e < 8; ++e) { XR[(c8 + e) * PW + b] = (bf16_t)vr[e]; XI[(c8 + e) * PW + b] = (bf16_t)vi[e]; } }
.LBB0_388:
	s_or_b64 exec, exec, s[0:1]
	v_readlane_b32 s0, v254, 9
	v_readlane_b32 s1, v254, 10
	s_andn2_b64 vcc, exec, s[0:1]
	s_waitcnt lgkmcnt(0)
	s_barrier
	s_cbranch_vccnz .LBB0_391
	v_and_b32_e32 v3, 0x7f, v2
	v_readlane_b32 s0, v254, 13
	v_lshlrev_b32_e32 v4, 12, v3
	v_mov_b32_e32 v5, v0
	v_readlane_b32 s1, v254, 14
	v_bfe_u32 v1, v2, 4, 2
	v_lshlrev_b32_e32 v6, 4, v1
	v_lshl_add_u64 v[52:53], s[0:1], 0, v[4:5]
	s_ashr_i32 s1, s10, 2
	s_and_b32 s0, s1, -16
	v_bfi_b32 v4, -16, s1, v2
	s_movk_i32 s1, 0x110
	v_mul_lo_u32 v5, v4, s1
	s_ashr_i32 s1, s0, 31
	s_lshl_b64 s[0:1], s[0:1], 1
	v_readlane_b32 s6, v254, 57
	v_readlane_b32 s7, v254, 59
	s_add_u32 s0, s76, s0
	v_lshlrev_b32_e32 v4, 3, v1
	v_add3_u32 v1, s6, v5, v6
	v_add3_u32 v80, s7, v5, v6
	s_addc_u32 s1, s77, s1
	v_mov_b32_e32 v5, v0
	v_lshl_add_u64 v[54:55], s[0:1], 0, v[4:5]
	v_ashrrev_i32_e32 v4, 4, v2
	v_and_b32_e32 v56, -8, v4
	s_movk_i32 s0, 0x88
	v_mul_lo_u32 v5, v56, s0
	v_add_lshl_u32 v5, v5, v3, 1
	v_or_b32_e32 v4, 7, v4
	v_add_u32_e32 v7, 0x110, v5
	v_mul_lo_u32 v4, v4, s0
	v_add_u32_e32 v83, s6, v7
	v_add_u32_e32 v84, s7, v7
	v_add_u32_e32 v7, 0x220, v5
	v_add_lshl_u32 v4, v4, v3, 1
	v_add_u32_e32 v85, s6, v7
	v_add_u32_e32 v86, s7, v7
	v_add_u32_e32 v7, 0x330, v5
	v_add_u32_e32 v95, s6, v4
	v_add_u32_e32 v96, s7, v4
	v_add_u32_e32 v4, 0x200, v2
	v_add_u32_e32 v87, s6, v7
	v_add_u32_e32 v88, s7, v7
	v_add_u32_e32 v7, 0x440, v5
	v_ashrrev_i32_e32 v4, 4, v4
	v_add_u32_e32 v81, s6, v5
	v_add_u32_e32 v82, s7, v5
	v_add_u32_e32 v89, s6, v7
	v_add_u32_e32 v90, s7, v7
	v_add_u32_e32 v7, 0x550, v5
	v_add_u32_e32 v5, 0x660, v5
	v_and_b32_e32 v58, -8, v4
	v_add_u32_e32 v93, s6, v5
	v_add_u32_e32 v94, s7, v5
	v_mul_lo_u32 v5, v58, s0
	v_add_lshl_u32 v5, v5, v3, 1
	v_or_b32_e32 v4, 7, v4
	v_add_u32_e32 v91, s6, v7
	v_add_u32_e32 v92, s7, v7
	v_add_u32_e32 v7, 0x110, v5
	v_mul_lo_u32 v4, v4, s0
	v_add_u32_e32 v99, s6, v7
	v_add_u32_e32 v100, s7, v7
	v_add_u32_e32 v7, 0x220, v5
	v_add_lshl_u32 v4, v4, v3, 1
	v_add_u32_e32 v101, s6, v7
	v_add_u32_e32 v102, s7, v7
	v_add_u32_e32 v7, 0x330, v5
	v_add_u32_e32 v111, s6, v4
	v_add_u32_e32 v112, s7, v4
	v_add_u32_e32 v4, 0x400, v2
	v_add_u32_e32 v103, s6, v7
	v_add_u32_e32 v104, s7, v7
	v_add_u32_e32 v7, 0x440, v5
	v_ashrrev_i32_e32 v4, 4, v4
	v_add_u32_e32 v97, s6, v5
	v_add_u32_e32 v98, s7, v5
	v_add_u32_e32 v105, s6, v7
	v_add_u32_e32 v106, s7, v7
	v_add_u32_e32 v7, 0x550, v5
	v_add_u32_e32 v5, 0x660, v5
	v_and_b32_e32 v60, -8, v4
	v_add_u32_e32 v109, s6, v5
	v_add_u32_e32 v110, s7, v5
	v_mul_lo_u32 v5, v60, s0
	v_add_lshl_u32 v5, v5, v3, 1
	v_and_b32_e32 v50, 15, v2
	v_add_u32_e32 v107, s6, v7
	v_add_u32_e32 v108, s7, v7
	v_add_u32_e32 v7, 0x110, v5
	v_or_b32_e32 v4, 7, v4
	v_add_u32_e32 v2, 0x600, v2
	v_add_u32_e32 v115, s6, v7
	v_add_u32_e32 v116, s7, v7
	v_add_u32_e32 v7, 0x220, v5
	v_mul_lo_u32 v4, v4, s0
	v_ashrrev_i32_e32 v2, 4, v2
	v_add_u32_e32 v117, s6, v7
	v_add_u32_e32 v118, s7, v7
	v_add_u32_e32 v7, 0x330, v5
	v_add_lshl_u32 v4, v4, v3, 1
	v_and_b32_e32 v62, -8, v2
	v_add_u32_e32 v119, s6, v7
	v_add_u32_e32 v120, s7, v7
	v_add_u32_e32 v7, 0x440, v5
	v_add_u32_e32 v127, s6, v4
	v_add_u32_e32 v128, s7, v4
	v_mul_lo_u32 v4, v62, s0
	v_add_u32_e32 v113, s6, v5
	v_add_u32_e32 v114, s7, v5
	v_add_u32_e32 v121, s6, v7
	v_add_u32_e32 v122, s7, v7
	v_add_u32_e32 v7, 0x550, v5
	v_add_u32_e32 v5, 0x660, v5
	v_add_lshl_u32 v4, v4, v3, 1
	v_add_u32_e32 v125, s6, v5
	v_add_u32_e32 v126, s7, v5
	v_add_u32_e32 v5, 0x110, v4
	v_or_b32_e32 v2, 7, v2
	v_add_u32_e32 v131, s6, v5
	v_add_u32_e32 v132, s7, v5
	v_add_u32_e32 v5, 0x220, v4
	v_mul_lo_u32 v2, v2, s0
	v_add_u32_e32 v133, s6, v5
	v_add_u32_e32 v134, s7, v5
	v_add_u32_e32 v5, 0x330, v4
	v_add_lshl_u32 v2, v2, v3, 1
	v_add_u32_e32 v135, s6, v5
	v_add_u32_e32 v136, s7, v5
	v_add_u32_e32 v5, 0x440, v4
	v_add_u32_e32 v143, s6, v2
	v_add_u32_e32 v144, s7, v2
	v_mul_u32_u24_e32 v2, 0x88, v50
	v_add_u32_e32 v129, s6, v4
	v_add_u32_e32 v130, s7, v4
	v_add_u32_e32 v137, s6, v5
	v_add_u32_e32 v138, s7, v5
	v_add_u32_e32 v5, 0x550, v4
	v_add_u32_e32 v4, 0x660, v4
	v_lshlrev_b32_e32 v2, 1, v2
	v_ashrrev_i32_e32 v57, 31, v56
	v_ashrrev_i32_e32 v59, 31, v58
	v_ashrrev_i32_e32 v61, 31, v60
	v_add_u32_e32 v123, s6, v7
	v_add_u32_e32 v124, s7, v7
	v_ashrrev_i32_e32 v63, 31, v62
	v_add_u32_e32 v139, s6, v5
	v_add_u32_e32 v140, s7, v5
	v_add_u32_e32 v141, s6, v4
	v_add_u32_e32 v142, s7, v4
	v_add3_u32 v145, 0, v6, v2
	v_mov_b32_e32 v51, v0
	v_or_b32_e32 v64, 16, v50
	v_mov_b32_e32 v65, v0
	v_or_b32_e32 v66, 32, v50
	v_mov_b32_e32 v67, v0
	v_or_b32_e32 v68, 48, v50
	v_mov_b32_e32 v69, v0
	v_or_b32_e32 v70, 64, v50
	v_mov_b32_e32 v71, v0
	v_or_b32_e32 v72, 0x50, v50
	v_mov_b32_e32 v73, v0
	v_or_b32_e32 v74, 0x60, v50
	v_mov_b32_e32 v75, v0
	v_or_b32_e32 v76, 0x70, v50
	v_mov_b32_e32 v77, v0
	v_readlane_b32 s6, v254, 40
	s_mov_b32 s7, s2
	s_ashr_i32 s98, s7, 3
	s_ashr_i32 s99, s98, 31
	s_lshl_b64 s[98:99], s[98:99], 19
	s_and_b32 s100, s6, 0x380
	s_lshl_b32 s100, s100, 1
	v_lshl_add_u64 v[162:163], v[52:53], 0, s[98:99]
	v_mov_b32_e32 v166, s100
	v_mov_b32_e32 v167, 0
	v_lshl_add_u64 v[162:163], v[162:163], 0, v[166:167]
	v_lshl_add_u64 v[164:165], v[56:57], 1, v[162:163]
	global_load_dwordx4 v[180:183], v[164:165], off
	global_load_dwordx4 v[184:187], v[164:165], off offset:2048
	v_lshl_add_u64 v[164:165], v[58:59], 1, v[162:163]
	global_load_dwordx4 v[188:191], v[164:165], off
	global_load_dwordx4 v[192:195], v[164:165], off offset:2048
	v_lshl_add_u64 v[164:165], v[60:61], 1, v[162:163]
	global_load_dwordx4 v[196:199], v[164:165], off
	global_load_dwordx4 v[200:203], v[164:165], off offset:2048
	v_lshl_add_u64 v[164:165], v[62:63], 1, v[162:163]
	global_load_dwordx4 v[204:207], v[164:165], off
	global_load_dwordx4 v[208:211], v[164:165], off offset:2048
	s_waitcnt vmcnt(0)
; __device__ __forceinline__ f32x4 mfma16(bf16x8 a, bf16x8 b, f32x4 c) { return __builtin_amdgcn_mfma_f32_16x16x32_bf16(a, b, c, 0, 0, 0); }
; __device__ void fft2_phase(int wv, const Params& p, unsigned char* lds) {
;     ...
;     for (int unit = blockIdx.x; unit < 2048; unit += gridDim.x) {
;         const int gi = unit >> 3, cb = unit & 7;
;         const int seq = gi < 64 ? 0 : (gi < 128 ? 1 : 2); const int ka = gi - (seq == 0 ? 0 : (seq == 1 ? 64 : 128)); const int N1 = seq == 2 ? 128 : 64;
;         const size_t sbase = (size_t)seq * 8192;
; #pragma unroll
;         for (int ps = 0; ps < 4; ++ps) { const int idx = tid + ps * NTHR, b = idx & 127, c8 = (idx >> 7) * 8;
;             const bf16_t* rp = A1 + ((size_t)gi * 128 + b) * 2048 + cb * 128 + c8; const bf16x8 vr = *(const bf16x8*)rp, vi = *(const bf16x8*)(rp + 1024);
; #pragma unroll
;             for (int e = 0; e < 8; ++e) { XR[(c8 + e) * PW + b] = (bf16_t)vr[e]; XI[(c8 + e) * PW + b] = (bf16_t)vi[e]; } }
;         __syncthreads();
;         bf16x8 xr[4], xi[4], nxr[4];
; #pragma unroll
;         for (int kk = 0; kk < 4; ++kk) { xr[kk] = *(const bf16x8*)(XR + (16 * w + lr) * PW + 32 * kk + 8 * lq); xi[kk] = *(const bf16x8*)(XI + (16 * w + lr) * PW + 32 * kk + 8 * lq);
;             union { bf16x8 v; unsigned u[4]; } t; t.v = xr[kk]; t.u[0] ^= 0x80008000u; t.u[1] ^= 0x80008000u; t.u[2] ^= 0x80008000u; t.u[3] ^= 0x80008000u; nxr[kk] = t.v; }
; #pragma unroll
;         for (int i = 0; i < 8; ++i) { f32x4 re = {0, 0, 0, 0}, im = {0, 0, 0, 0};
; #pragma unroll
;             for (int kk = 0; kk < 4; ++kk) { const bf16x8 cf = *(const bf16x8*)(CT + (16 * i + lr) * PW + 32 * kk + 8 * lq), sf = *(const bf16x8*)(ST + (16 * i + lr) * PW + 32 * kk + 8 * lq);
;                 re = mfma16(xr[kk], cf, re); re = mfma16(xi[kk], sf, re); im = mfma16(xi[kk], cf, im); im = mfma16(nxr[kk], sf, im); }
.LBB0_390:
	s_waitcnt vmcnt(16)
.Lfft2_entry:
	s_ashr_i32 s14, s7, 3
	s_cmpk_lt_i32 s14, 0x80
	s_cselect_b32 s0, 1, 2
	s_and_b32 s1, s7, 0xfffffe00
	s_cmpk_eq_i32 s1, 0x200
	s_movk_i32 s1, 0xff80
	s_cselect_b32 s1, 0xffffffc0, s1
	s_cmp_gt_i32 s14, 63
	s_cselect_b32 s10, s0, 0
	s_cselect_b32 s0, s1, 0
	s_ashr_i32 s15, s14, 31
	s_add_i32 s0, s0, s14
	s_lshl_b64 s[14:15], s[14:15], 19
	s_and_b32 s11, s6, 0x380
	v_lshl_add_u64 v[2:3], v[52:53], 0, s[14:15]
	s_lshl_b32 s36, s11, 1
	v_lshl_add_u64 v[2:3], v[2:3], 0, s[36:37]
	s_lshl_b32 s1, s10, 13
	s_ashr_i32 s11, s0, 31
	s_add_u32 s0, s0, s1
	s_addc_u32 s1, s11, 0
	s_cmp_eq_u32 s10, 2
	s_cselect_b32 s10, 7, 6
	v_lshl_add_u64 v[78:79], v[54:55], 0, s[36:37]
	s_add_i32 s7, s7, s34
	s_add_i32 s6, s6, s92
	s_cmpk_lt_i32 s7, 0x800
	s_cselect_b32 s101, 1, 0
	ds_write_b16 v81, v180
	ds_write_b16 v82, v184
	ds_write_b16_d16_hi v83, v180
	ds_write_b16_d16_hi v84, v184
	ds_write_b16 v85, v181
	ds_write_b16 v86, v185
	ds_write_b16_d16_hi v87, v181
	ds_write_b16_d16_hi v88, v185
	ds_write_b16 v89, v182
	ds_write_b16 v90, v186
	ds_write_b16_d16_hi v91, v182
	ds_write_b16_d16_hi v92, v186
	ds_write_b16 v93, v183
	ds_write_b16 v94, v187
	ds_write_b16_d16_hi v95, v183
	ds_write_b16_d16_hi v96, v187
	ds_write_b16 v97, v188
	ds_write_b16 v98, v192
	ds_write_b16_d16_hi v99, v188
	ds_write_b16_d16_hi v100, v192
	ds_write_b16 v101, v189
	ds_write_b16 v102, v193
	ds_write_b16_d16_hi v103, v189
	ds_write_b16_d16_hi v104, v193
	ds_write_b16 v105, v190
	ds_write_b16 v106, v194
	ds_write_b16_d16_hi v107, v190
	ds_write_b16_d16_hi v108, v194
	ds_write_b16 v109, v191
	ds_write_b16 v110, v195
	ds_write_b16_d16_hi v111, v191
	ds_write_b16_d16_hi v112, v195
	ds_write_b16 v113, v196
	ds_write_b16 v114, v200
	ds_write_b16_d16_hi v115, v196
	ds_write_b16_d16_hi v116, v200
	ds_write_b16 v117, v197
	ds_write_b16 v118, v201
	ds_write_b16_d16_hi v119, v197
	ds_write_b16_d16_hi v120, v201
	ds_write_b16 v121, v198
	ds_write_b16 v122, v202
	ds_write_b16_d16_hi v123, v198
	ds_write_b16_d16_hi v124, v202
	ds_write_b16 v125, v199
	ds_write_b16 v126, v203
	ds_write_b16_d16_hi v127, v199
	ds_write_b16_d16_hi v128, v203
	ds_write_b16 v129, v204
	ds_write_b16 v130, v208
	ds_write_b16_d16_hi v131, v204
	ds_write_b16_d16_hi v132, v208
	ds_write_b16 v133, v205
	ds_write_b16 v134, v209
	ds_write_b16_d16_hi v135, v205
	ds_write_b16_d16_hi v136, v209
	ds_write_b16 v137, v206
	ds_write_b16 v138, v210
	ds_write_b16_d16_hi v139, v206
	ds_write_b16_d16_hi v140, v210
	ds_write_b16 v141, v207
	ds_write_b16 v142, v211
	ds_write_b16_d16_hi v143, v207
	ds_write_b16_d16_hi v144, v211
	s_waitcnt lgkmcnt(0)
	s_barrier
	s_cmp_lg_u32 s101, 0
	s_cbranch_scc0 .Lfft2_nopf
	s_ashr_i32 s98, s7, 3
	s_ashr_i32 s99, s98, 31
	s_lshl_b64 s[98:99], s[98:99], 19
	s_and_b32 s100, s6, 0x380
	s_lshl_b32 s100, s100, 1
	v_lshl_add_u64 v[162:163], v[52:53], 0, s[98:99]
	v_mov_b32_e32 v166, s100
	v_mov_b32_e32 v167, 0
	v_lshl_add_u64 v[162:163], v[162:163], 0, v[166:167]
	v_lshl_add_u64 v[164:165], v[56:57], 1, v[162:163]
	global_load_dwordx4 v[180:183], v[164:165], off
	global_load_dwordx4 v[184:187], v[164:165], off offset:2048
	v_lshl_add_u64 v[164:165], v[58:59], 1, v[162:163]
	global_load_dwordx4 v[188:191], v[164:165], off
	global_load_dwordx4 v[192:195], v[164:165], off offset:2048
	v_lshl_add_u64 v[164:165], v[60:61], 1, v[162:163]
	global_load_dwordx4 v[196:199], v[164:165], off
	global_load_dwordx4 v[200:203], v[164:165], off offset:2048
	v_lshl_add_u64 v[164:165], v[62:63], 1, v[162:163]
	global_load_dwordx4 v[204:207], v[164:165], off
	global_load_dwordx4 v[208:211], v[164:165], off offset:2048
.Lfft2_nopf:
	ds_read_b128 v[46:49], v1
	ds_read_b128 v[38:41], v80
	ds_read_b128 v[34:37], v1 offset:64
	ds_read_b128 v[30:33], v80 offset:64
	ds_read_b128 v[22:25], v1 offset:128
	ds_read_b128 v[14:17], v80 offset:128
	ds_read_b128 v[10:13], v1 offset:192
	ds_read_b128 v[2:5], v80 offset:192
	ds_read_b128 v[146:149], v145
	ds_read_b128 v[150:153], v145 offset:34816
	s_waitcnt lgkmcnt(9)
	v_xor_b32_e32 v42, 0x80008000, v46
	v_xor_b32_e32 v43, 0x80008000, v47
	v_xor_b32_e32 v44, 0x80008000, v48
	v_xor_b32_e32 v45, 0x80008000, v49
	s_waitcnt lgkmcnt(1)
	v_mfma_f32_16x16x32_bf16 v[154:157], v[46:49], v[146:149], 0
	v_xor_b32_e32 v26, 0x80008000, v34
	v_xor_b32_e32 v27, 0x80008000, v35
	v_xor_b32_e32 v28, 0x80008000, v36
	v_mfma_f32_16x16x32_bf16 v[146:149], v[38:41], v[146:149], 0
	v_xor_b32_e32 v29, 0x80008000, v37
	v_xor_b32_e32 v18, 0x80008000, v22
	v_xor_b32_e32 v19, 0x80008000, v23
	s_waitcnt lgkmcnt(0)
	v_mfma_f32_16x16x32_bf16 v[154:157], v[38:41], v[150:153], v[154:157]
	v_xor_b32_e32 v20, 0x80008000, v24
	v_xor_b32_e32 v21, 0x80008000, v25
	v_xor_b32_e32 v6, 0x80008000, v10
	v_mfma_f32_16x16x32_bf16 v[146:149], v[42:45], v[150:153], v[146:149]
	ds_read_b128 v[150:153], v145 offset:64
	ds_read_b128 v[158:161], v145 offset:34880
	v_xor_b32_e32 v7, 0x80008000, v11
	v_xor_b32_e32 v8, 0x80008000, v12
	s_waitcnt lgkmcnt(1)
	v_mfma_f32_16x16x32_bf16 v[154:157], v[34:37], v[150:153], v[154:157]
	v_xor_b32_e32 v9, 0x80008000, v13
	v_mfma_f32_16x16x32_bf16 v[146:149], v[30:33], v[150:153], v[146:149]
	s_waitcnt lgkmcnt(0)
	v_mfma_f32_16x16x32_bf16 v[154:157], v[30:33], v[158:161], v[154:157]
	v_mfma_f32_16x16x32_bf16 v[146:149], v[26:29], v[158:161], v[146:149]
	ds_read_b128 v[150:153], v145 offset:128
	ds_read_b128 v[158:161], v145 offset:34944
	s_waitcnt lgkmcnt(1)
	v_mfma_f32_16x16x32_bf16 v[154:157], v[22:25], v[150:153], v[154:157]
	v_mfma_f32_16x16x32_bf16 v[146:149], v[14:17], v[150:153], v[146:149]
	s_waitcnt lgkmcnt(0)
; __device__ __forceinline__ unsigned cvt_pk_bf16(float lo, float hi) { const f2_t v = {lo, hi}; const bf2_t b = __builtin_convertvector(v, bf2_t); return __builtin_bit_cast(unsigned, b); }
; __device__ __forceinline__ f32x4 mfma16(bf16x8 a, bf16x8 b, f32x4 c) { return __builtin_amdgcn_mfma_f32_16x16x32_bf16(a, b, c, 0, 0, 0); }
; __device__ void fft2_phase(int wv, const Params& p, unsigned char* lds) {
;     ...
;         for (int i = 0; i < 8; ++i) { f32x4 re = {0, 0, 0, 0}, im = {0, 0, 0, 0};
; #pragma unroll
;             for (int kk = 0; kk < 4; ++kk) { const bf16x8 cf = *(const bf16x8*)(CT + (16 * i + lr) * PW + 32 * kk + 8 * lq), sf = *(const bf16x8*)(ST + (16 * i + lr) * PW + 32 * kk + 8 * lq);
;                 re = mfma16(xr[kk], cf, re); re = mfma16(xi[kk], sf, re); im = mfma16(xi[kk], cf, im); im = mfma16(nxr[kk], sf, im); }
;             const int kb = 16 * i + lr;
;             bf16_t* op = Y + (sbase + (size_t)N1 * kb + ka) * 2048 + cb * 128 + 16 * w + 4 * lq;
;             u32x2 o; o.x = cvt_pk_bf16(re[0], re[1]); o.y = cvt_pk_bf16(re[2], re[3]); *(u32x2*)op = o;
;             o.x = cvt_pk_bf16(im[0], im[1]); o.y = cvt_pk_bf16(im[2], im[3]); *(u32x2*)(op + 1024) = o; }
	v_mfma_f32_16x16x32_bf16 v[154:157], v[14:17], v[158:161], v[154:157]
	v_mfma_f32_16x16x32_bf16 v[146:149], v[18:21], v[158:161], v[146:149]
	ds_read_b128 v[150:153], v145 offset:192
	ds_read_b128 v[158:161], v145 offset:35008
	s_waitcnt lgkmcnt(1)
	v_mfma_f32_16x16x32_bf16 v[154:157], v[10:13], v[150:153], v[154:157]
	v_mfma_f32_16x16x32_bf16 v[146:149], v[2:5], v[150:153], v[146:149]
	v_lshlrev_b64 v[150:151], s10, v[50:51]
	v_lshl_add_u64 v[150:151], s[0:1], 0, v[150:151]
	v_lshlrev_b64 v[150:151], 12, v[150:151]
	s_waitcnt lgkmcnt(0)
	v_mfma_f32_16x16x32_bf16 v[154:157], v[2:5], v[158:161], v[154:157]
	v_lshl_add_u64 v[150:151], v[78:79], 0, v[150:151]
	v_mfma_f32_16x16x32_bf16 v[146:149], v[6:9], v[158:161], v[146:149]
	s_nop 5
	v_cvt_pk_bf16_f32 v152, v154, v155
	v_cvt_pk_bf16_f32 v153, v156, v157
	v_cvt_pk_bf16_f32 v146, v146, v147
	v_cvt_pk_bf16_f32 v147, v148, v149
	global_store_dwordx2 v[150:151], v[152:153], off
	global_store_dwordx2 v[150:151], v[146:147], off offset:2048
	ds_read_b128 v[146:149], v145 offset:4352
	ds_read_b128 v[150:153], v145 offset:39168
	s_waitcnt lgkmcnt(1)
	v_mfma_f32_16x16x32_bf16 v[154:157], v[46:49], v[146:149], 0
	v_mfma_f32_16x16x32_bf16 v[146:149], v[38:41], v[146:149], 0
	s_waitcnt lgkmcnt(0)
	v_mfma_f32_16x16x32_bf16 v[154:157], v[38:41], v[150:153], v[154:157]
	v_mfma_f32_16x16x32_bf16 v[146:149], v[42:45], v[150:153], v[146:149]
	ds_read_b128 v[150:153], v145 offset:4416
	ds_read_b128 v[158:161], v145 offset:39232
	s_waitcnt lgkmcnt(1)
	v_mfma_f32_16x16x32_bf16 v[154:157], v[34:37], v[150:153], v[154:157]
	v_mfma_f32_16x16x32_bf16 v[146:149], v[30:33], v[150:153], v[146:149]
	s_waitcnt lgkmcnt(0)
	v_mfma_f32_16x16x32_bf16 v[154:157], v[30:33], v[158:161], v[154:157]
	v_mfma_f32_16x16x32_bf16 v[146:149], v[26:29], v[158:161], v[146:149]
	ds_read_b128 v[150:153], v145 offset:4480
	ds_read_b128 v[158:161], v145 offset:39296
	s_waitcnt lgkmcnt(1)
	v_mfma_f32_16x16x32_bf16 v[154:157], v[22:25], v[150:153], v[154:157]
	v_mfma_f32_16x16x32_bf16 v[146:149], v[14:17], v[150:153], v[146:149]
	s_waitcnt lgkmcnt(0)
	v_mfma_f32_16x16x32_bf16 v[154:157], v[14:17], v[158:161], v[154:157]
	v_mfma_f32_16x16x32_bf16 v[146:149], v[18:21], v[158:161], v[146:149]
	ds_read_b128 v[150:153], v145 offset:4544
	ds_read_b128 v[158:161], v145 offset:39360
	s_waitcnt lgkmcnt(1)
	v_mfma_f32_16x16x32_bf16 v[154:157], v[10:13], v[150:153], v[154:157]
	v_mfma_f32_16x16x32_bf16 v[146:149], v[2:5], v[150:153], v[146:149]
	v_lshlrev_b64 v[150:151], s10, v[64:65]
	v_lshl_add_u64 v[150:151], s[0:1], 0, v[150:151]
	v_lshlrev_b64 v[150:151], 12, v[150:151]
	s_waitcnt lgkmcnt(0)
	v_mfma_f32_16x16x32_bf16 v[154:157], v[2:5], v[158:161], v[154:157]
	v_lshl_add_u64 v[150:151], v[78:79], 0, v[150:151]
	v_mfma_f32_16x16x32_bf16 v[146:149], v[6:9], v[158:161], v[146:149]
	s_nop 5
	v_cvt_pk_bf16_f32 v152, v154, v155
	v_cvt_pk_bf16_f32 v153, v156, v157
	v_cvt_pk_bf16_f32 v146, v146, v147
	v_cvt_pk_bf16_f32 v147, v148, v149
	global_store_dwordx2 v[150:151], v[152:153], off
	global_store_dwordx2 v[150:151], v[146:147], off offset:2048
	ds_read_b128 v[146:149], v145 offset:8704
	ds_read_b128 v[150:153], v145 offset:43520
	s_waitcnt lgkmcnt(1)
	v_mfma_f32_16x16x32_bf16 v[154:157], v[46:49], v[146:149], 0
	v_mfma_f32_16x16x32_bf16 v[146:149], v[38:41], v[146:149], 0
	s_waitcnt lgkmcnt(0)
	v_mfma_f32_16x16x32_bf16 v[154:157], v[38:41], v[150:153], v[154:157]
	v_mfma_f32_16x16x32_bf16 v[146:149], v[42:45], v[150:153], v[146:149]
	ds_read_b128 v[150:153], v145 offset:8768
	ds_read_b128 v[158:161], v145 offset:43584
	s_waitcnt lgkmcnt(1)
	v_mfma_f32_16x16x32_bf16 v[154:157], v[34:37], v[150:153], v[154:157]
	v_mfma_f32_16x16x32_bf16 v[146:149], v[30:33], v[150:153], v[146:149]
	s_waitcnt lgkmcnt(0)
	v_mfma_f32_16x16x32_bf16 v[154:157], v[30:33], v[158:161], v[154:157]
	v_mfma_f32_16x16x32_bf16 v[146:149], v[26:29], v[158:161], v[146:149]
	ds_read_b128 v[150:153], v145 offset:8832
	ds_read_b128 v[158:161], v145 offset:43648
	s_waitcnt lgkmcnt(1)
	v_mfma_f32_16x16x32_bf16 v[154:157], v[22:25], v[150:153], v[154:157]
	v_mfma_f32_16x16x32_bf16 v[146:149], v[14:17], v[150:153], v[146:149]
	s_waitcnt lgkmcnt(0)
	v_mfma_f32_16x16x32_bf16 v[154:157], v[14:17], v[158:161], v[154:157]
	v_mfma_f32_16x16x32_bf16 v[146:149], v[18:21], v[158:161], v[146:149]
	ds_read_b128 v[150:153], v145 offset:8896
	ds_read_b128 v[158:161], v145 offset:43712
	s_waitcnt lgkmcnt(1)
	v_mfma_f32_16x16x32_bf16 v[154:157], v[10:13], v[150:153], v[154:157]
	v_mfma_f32_16x16x32_bf16 v[146:149], v[2:5], v[150:153], v[146:149]
	v_lshlrev_b64 v[150:151], s10, v[66:67]
	v_lshl_add_u64 v[150:151], s[0:1], 0, v[150:151]
	v_lshlrev_b64 v[150:151], 12, v[150:151]
	s_waitcnt lgkmcnt(0)
	v_mfma_f32_16x16x32_bf16 v[154:157], v[2:5], v[158:161], v[154:157]
	v_lshl_add_u64 v[150:151], v[78:79], 0, v[150:151]
	v_mfma_f32_16x16x32_bf16 v[146:149], v[6:9], v[158:161], v[146:149]
	s_nop 5
	v_cvt_pk_bf16_f32 v152, v154, v155
	v_cvt_pk_bf16_f32 v153, v156, v157
	v_cvt_pk_bf16_f32 v146, v146, v147
	v_cvt_pk_bf16_f32 v147, v148, v149
	global_store_dwordx2 v[150:151], v[152:153], off
	global_store_dwordx2 v[150:151], v[146:147], off offset:2048
	ds_read_b128 v[146:149], v145 offset:13056
	ds_read_b128 v[150:153], v145 offset:47872
	s_waitcnt lgkmcnt(1)
	v_mfma_f32_16x16x32_bf16 v[154:157], v[46:49], v[146:149], 0
	v_mfma_f32_16x16x32_bf16 v[146:149], v[38:41], v[146:149], 0
	s_waitcnt lgkmcnt(0)
	v_mfma_f32_16x16x32_bf16 v[154:157], v[38:41], v[150:153], v[154:157]
	v_mfma_f32_16x16x32_bf16 v[146:149], v[42:45], v[150:153], v[146:149]
	ds_read_b128 v[150:153], v145 offset:13120
	ds_read_b128 v[158:161], v145 offset:47936
	s_waitcnt lgkmcnt(1)
; __device__ __forceinline__ unsigned cvt_pk_bf16(float lo, float hi) { const f2_t v = {lo, hi}; const bf2_t b = __builtin_convertvector(v, bf2_t); return __builtin_bit_cast(unsigned, b); }
; __device__ __forceinline__ f32x4 mfma16(bf16x8 a, bf16x8 b, f32x4 c) { return __builtin_amdgcn_mfma_f32_16x16x32_bf16(a, b, c, 0, 0, 0); }
; __device__ void fft2_phase(int wv, const Params& p, unsigned char* lds) {
;     ...
;         for (int i = 0; i < 8; ++i) { f32x4 re = {0, 0, 0, 0}, im = {0, 0, 0, 0};
; #pragma unroll
;             for (int kk = 0; kk < 4; ++kk) { const bf16x8 cf = *(const bf16x8*)(CT + (16 * i + lr) * PW + 32 * kk + 8 * lq), sf = *(const bf16x8*)(ST + (16 * i + lr) * PW + 32 * kk + 8 * lq);
;                 re = mfma16(xr[kk], cf, re); re = mfma16(xi[kk], sf, re); im = mfma16(xi[kk], cf, im); im = mfma16(nxr[kk], sf, im); }
;             const int kb = 16 * i + lr;
;             bf16_t* op = Y + (sbase + (size_t)N1 * kb + ka) * 2048 + cb * 128 + 16 * w + 4 * lq;
;             u32x2 o; o.x = cvt_pk_bf16(re[0], re[1]); o.y = cvt_pk_bf16(re[2], re[3]); *(u32x2*)op = o;
;             o.x = cvt_pk_bf16(im[0], im[1]); o.y = cvt_pk_bf16(im[2], im[3]); *(u32x2*)(op + 1024) = o; }
	v_mfma_f32_16x16x32_bf16 v[154:157], v[34:37], v[150:153], v[154:157]
	v_mfma_f32_16x16x32_bf16 v[146:149], v[30:33], v[150:153], v[146:149]
	s_waitcnt lgkmcnt(0)
	v_mfma_f32_16x16x32_bf16 v[154:157], v[30:33], v[158:161], v[154:157]
	v_mfma_f32_16x16x32_bf16 v[146:149], v[26:29], v[158:161], v[146:149]
	ds_read_b128 v[150:153], v145 offset:13184
	ds_read_b128 v[158:161], v145 offset:48000
	s_waitcnt lgkmcnt(1)
	v_mfma_f32_16x16x32_bf16 v[154:157], v[22:25], v[150:153], v[154:157]
	v_mfma_f32_16x16x32_bf16 v[146:149], v[14:17], v[150:153], v[146:149]
	s_waitcnt lgkmcnt(0)
	v_mfma_f32_16x16x32_bf16 v[154:157], v[14:17], v[158:161], v[154:157]
	v_mfma_f32_16x16x32_bf16 v[146:149], v[18:21], v[158:161], v[146:149]
	ds_read_b128 v[150:153], v145 offset:13248
	ds_read_b128 v[158:161], v145 offset:48064
	s_waitcnt lgkmcnt(1)
	v_mfma_f32_16x16x32_bf16 v[154:157], v[10:13], v[150:153], v[154:157]
	v_mfma_f32_16x16x32_bf16 v[146:149], v[2:5], v[150:153], v[146:149]
	v_lshlrev_b64 v[150:151], s10, v[68:69]
	v_lshl_add_u64 v[150:151], s[0:1], 0, v[150:151]
	v_lshlrev_b64 v[150:151], 12, v[150:151]
	s_waitcnt lgkmcnt(0)
	v_mfma_f32_16x16x32_bf16 v[154:157], v[2:5], v[158:161], v[154:157]
	v_lshl_add_u64 v[150:151], v[78:79], 0, v[150:151]
	v_mfma_f32_16x16x32_bf16 v[146:149], v[6:9], v[158:161], v[146:149]
	s_nop 5
	v_cvt_pk_bf16_f32 v152, v154, v155
	v_cvt_pk_bf16_f32 v153, v156, v157
	v_cvt_pk_bf16_f32 v146, v146, v147
	v_cvt_pk_bf16_f32 v147, v148, v149
	global_store_dwordx2 v[150:151], v[152:153], off
	global_store_dwordx2 v[150:151], v[146:147], off offset:2048
	ds_read_b128 v[146:149], v145 offset:17408
	ds_read_b128 v[150:153], v145 offset:52224
	s_waitcnt lgkmcnt(1)
	v_mfma_f32_16x16x32_bf16 v[154:157], v[46:49], v[146:149], 0
	v_mfma_f32_16x16x32_bf16 v[146:149], v[38:41], v[146:149], 0
	s_waitcnt lgkmcnt(0)
	v_mfma_f32_16x16x32_bf16 v[154:157], v[38:41], v[150:153], v[154:157]
	v_mfma_f32_16x16x32_bf16 v[146:149], v[42:45], v[150:153], v[146:149]
	ds_read_b128 v[150:153], v145 offset:17472
	ds_read_b128 v[158:161], v145 offset:52288
	s_waitcnt lgkmcnt(1)
	v_mfma_f32_16x16x32_bf16 v[154:157], v[34:37], v[150:153], v[154:157]
	v_mfma_f32_16x16x32_bf16 v[146:149], v[30:33], v[150:153], v[146:149]
	s_waitcnt lgkmcnt(0)
	v_mfma_f32_16x16x32_bf16 v[154:157], v[30:33], v[158:161], v[154:157]
	v_mfma_f32_16x16x32_bf16 v[146:149], v[26:29], v[158:161], v[146:149]
	ds_read_b128 v[150:153], v145 offset:17536
	ds_read_b128 v[158:161], v145 offset:52352
	s_waitcnt lgkmcnt(1)
	v_mfma_f32_16x16x32_bf16 v[154:157], v[22:25], v[150:153], v[154:157]
	v_mfma_f32_16x16x32_bf16 v[146:149], v[14:17], v[150:153], v[146:149]
	s_waitcnt lgkmcnt(0)
	v_mfma_f32_16x16x32_bf16 v[154:157], v[14:17], v[158:161], v[154:157]
	v_mfma_f32_16x16x32_bf16 v[146:149], v[18:21], v[158:161], v[146:149]
	ds_read_b128 v[150:153], v145 offset:17600
	ds_read_b128 v[158:161], v145 offset:52416
	s_waitcnt lgkmcnt(1)
	v_mfma_f32_16x16x32_bf16 v[154:157], v[10:13], v[150:153], v[154:157]
	v_mfma_f32_16x16x32_bf16 v[146:149], v[2:5], v[150:153], v[146:149]
	v_lshlrev_b64 v[150:151], s10, v[70:71]
	v_lshl_add_u64 v[150:151], s[0:1], 0, v[150:151]
	v_lshlrev_b64 v[150:151], 12, v[150:151]
	s_waitcnt lgkmcnt(0)
	v_mfma_f32_16x16x32_bf16 v[154:157], v[2:5], v[158:161], v[154:157]
	v_lshl_add_u64 v[150:151], v[78:79], 0, v[150:151]
	v_mfma_f32_16x16x32_bf16 v[146:149], v[6:9], v[158:161], v[146:149]
	s_nop 5
	v_cvt_pk_bf16_f32 v152, v154, v155
	v_cvt_pk_bf16_f32 v153, v156, v157
	v_cvt_pk_bf16_f32 v146, v146, v147
	v_cvt_pk_bf16_f32 v147, v148, v149
	global_store_dwordx2 v[150:151], v[152:153], off
	global_store_dwordx2 v[150:151], v[146:147], off offset:2048
	ds_read_b128 v[146:149], v145 offset:21760
	ds_read_b128 v[150:153], v145 offset:56576
	s_waitcnt lgkmcnt(1)
	v_mfma_f32_16x16x32_bf16 v[154:157], v[46:49], v[146:149], 0
	v_mfma_f32_16x16x32_bf16 v[146:149], v[38:41], v[146:149], 0
	s_waitcnt lgkmcnt(0)
	v_mfma_f32_16x16x32_bf16 v[154:157], v[38:41], v[150:153], v[154:157]
	v_mfma_f32_16x16x32_bf16 v[146:149], v[42:45], v[150:153], v[146:149]
	ds_read_b128 v[150:153], v145 offset:21824
	ds_read_b128 v[158:161], v145 offset:56640
	s_waitcnt lgkmcnt(1)
	v_mfma_f32_16x16x32_bf16 v[154:157], v[34:37], v[150:153], v[154:157]
	v_mfma_f32_16x16x32_bf16 v[146:149], v[30:33], v[150:153], v[146:149]
	s_waitcnt lgkmcnt(0)
	v_mfma_f32_16x16x32_bf16 v[154:157], v[30:33], v[158:161], v[154:157]
	v_mfma_f32_16x16x32_bf16 v[146:149], v[26:29], v[158:161], v[146:149]
	ds_read_b128 v[150:153], v145 offset:21888
	ds_read_b128 v[158:161], v145 offset:56704
	s_waitcnt lgkmcnt(1)
	v_mfma_f32_16x16x32_bf16 v[154:157], v[22:25], v[150:153], v[154:157]
	v_mfma_f32_16x16x32_bf16 v[146:149], v[14:17], v[150:153], v[146:149]
	s_waitcnt lgkmcnt(0)
	v_mfma_f32_16x16x32_bf16 v[154:157], v[14:17], v[158:161], v[154:157]
	v_mfma_f32_16x16x32_bf16 v[146:149], v[18:21], v[158:161], v[146:149]
	ds_read_b128 v[150:153], v145 offset:21952
	ds_read_b128 v[158:161], v145 offset:56768
	s_waitcnt lgkmcnt(1)
; __device__ __forceinline__ unsigned cvt_pk_bf16(float lo, float hi) { const f2_t v = {lo, hi}; const bf2_t b = __builtin_convertvector(v, bf2_t); return __builtin_bit_cast(unsigned, b); }
; __device__ void fft2_phase(int wv, const Params& p, unsigned char* lds) {
;     ...
;             const int kb = 16 * i + lr;
;             bf16_t* op = Y + (sbase + (size_t)N1 * kb + ka) * 2048 + cb * 128 + 16 * w + 4 * lq;
;             u32x2 o; o.x = cvt_pk_bf16(re[0], re[1]); o.y = cvt_pk_bf16(re[2], re[3]); *(u32x2*)op = o;
;             o.x = cvt_pk_bf16(im[0], im[1]); o.y = cvt_pk_bf16(im[2], im[3]); *(u32x2*)(op + 1024) = o; }
;         __syncthreads();
;     }
	v_mfma_f32_16x16x32_bf16 v[154:157], v[10:13], v[150:153], v[154:157]
	v_mfma_f32_16x16x32_bf16 v[146:149], v[2:5], v[150:153], v[146:149]
	v_lshlrev_b64 v[150:151], s10, v[72:73]
	v_lshl_add_u64 v[150:151], s[0:1], 0, v[150:151]
	v_lshlrev_b64 v[150:151], 12, v[150:151]
	s_waitcnt lgkmcnt(0)
	v_mfma_f32_16x16x32_bf16 v[154:157], v[2:5], v[158:161], v[154:157]
	v_lshl_add_u64 v[150:151], v[78:79], 0, v[150:151]
	v_mfma_f32_16x16x32_bf16 v[146:149], v[6:9], v[158:161], v[146:149]
	s_nop 5
	v_cvt_pk_bf16_f32 v152, v154, v155
	v_cvt_pk_bf16_f32 v153, v156, v157
	v_cvt_pk_bf16_f32 v146, v146, v147
	v_cvt_pk_bf16_f32 v147, v148, v149
	global_store_dwordx2 v[150:151], v[152:153], off
	global_store_dwordx2 v[150:151], v[146:147], off offset:2048
	ds_read_b128 v[146:149], v145 offset:26112
	ds_read_b128 v[150:153], v145 offset:60928
	s_waitcnt lgkmcnt(1)
	v_mfma_f32_16x16x32_bf16 v[154:157], v[46:49], v[146:149], 0
	v_mfma_f32_16x16x32_bf16 v[146:149], v[38:41], v[146:149], 0
	s_waitcnt lgkmcnt(0)
	v_mfma_f32_16x16x32_bf16 v[154:157], v[38:41], v[150:153], v[154:157]
	v_mfma_f32_16x16x32_bf16 v[146:149], v[42:45], v[150:153], v[146:149]
	ds_read_b128 v[150:153], v145 offset:26176
	ds_read_b128 v[158:161], v145 offset:60992
	s_waitcnt lgkmcnt(1)
	v_mfma_f32_16x16x32_bf16 v[154:157], v[34:37], v[150:153], v[154:157]
	v_mfma_f32_16x16x32_bf16 v[146:149], v[30:33], v[150:153], v[146:149]
	s_waitcnt lgkmcnt(0)
	v_mfma_f32_16x16x32_bf16 v[154:157], v[30:33], v[158:161], v[154:157]
	v_mfma_f32_16x16x32_bf16 v[146:149], v[26:29], v[158:161], v[146:149]
	ds_read_b128 v[150:153], v145 offset:26240
	ds_read_b128 v[158:161], v145 offset:61056
	s_waitcnt lgkmcnt(1)
	v_mfma_f32_16x16x32_bf16 v[154:157], v[22:25], v[150:153], v[154:157]
	v_mfma_f32_16x16x32_bf16 v[146:149], v[14:17], v[150:153], v[146:149]
	s_waitcnt lgkmcnt(0)
	v_mfma_f32_16x16x32_bf16 v[154:157], v[14:17], v[158:161], v[154:157]
	v_mfma_f32_16x16x32_bf16 v[146:149], v[18:21], v[158:161], v[146:149]
	ds_read_b128 v[150:153], v145 offset:26304
	ds_read_b128 v[158:161], v145 offset:61120
	s_waitcnt lgkmcnt(1)
	v_mfma_f32_16x16x32_bf16 v[154:157], v[10:13], v[150:153], v[154:157]
	v_mfma_f32_16x16x32_bf16 v[146:149], v[2:5], v[150:153], v[146:149]
	v_lshlrev_b64 v[150:151], s10, v[74:75]
	v_lshl_add_u64 v[150:151], s[0:1], 0, v[150:151]
	v_lshlrev_b64 v[150:151], 12, v[150:151]
	s_waitcnt lgkmcnt(0)
	v_mfma_f32_16x16x32_bf16 v[154:157], v[2:5], v[158:161], v[154:157]
	v_lshl_add_u64 v[150:151], v[78:79], 0, v[150:151]
	v_mfma_f32_16x16x32_bf16 v[146:149], v[6:9], v[158:161], v[146:149]
	s_nop 5
	v_cvt_pk_bf16_f32 v152, v154, v155
	v_cvt_pk_bf16_f32 v153, v156, v157
	v_cvt_pk_bf16_f32 v146, v146, v147
	v_cvt_pk_bf16_f32 v147, v148, v149
	global_store_dwordx2 v[150:151], v[152:153], off
	global_store_dwordx2 v[150:151], v[146:147], off offset:2048
	ds_read_b128 v[146:149], v145 offset:30464
	ds_read_b128 v[150:153], v145 offset:65280
	s_waitcnt lgkmcnt(1)
	v_mfma_f32_16x16x32_bf16 v[46:49], v[46:49], v[146:149], 0
	s_waitcnt lgkmcnt(0)
	v_mfma_f32_16x16x32_bf16 v[46:49], v[38:41], v[150:153], v[46:49]
	v_mfma_f32_16x16x32_bf16 v[38:41], v[38:41], v[146:149], 0
	v_mfma_f32_16x16x32_bf16 v[38:41], v[42:45], v[150:153], v[38:41]
	ds_read_b128 v[42:45], v145 offset:30528
	ds_read_b128 v[146:149], v145 offset:65344
	s_waitcnt lgkmcnt(1)
	v_mfma_f32_16x16x32_bf16 v[34:37], v[34:37], v[42:45], v[46:49]
	s_waitcnt lgkmcnt(0)
	v_mfma_f32_16x16x32_bf16 v[34:37], v[30:33], v[146:149], v[34:37]
	v_mfma_f32_16x16x32_bf16 v[30:33], v[30:33], v[42:45], v[38:41]
	v_mfma_f32_16x16x32_bf16 v[26:29], v[26:29], v[146:149], v[30:33]
	s_nop 6
	ds_read_b128 v[30:33], v145 offset:30592
	ds_read_b128 v[38:41], v145 offset:65408
	s_waitcnt lgkmcnt(1)
	v_mfma_f32_16x16x32_bf16 v[22:25], v[22:25], v[30:33], v[34:37]
	s_waitcnt lgkmcnt(0)
	v_mfma_f32_16x16x32_bf16 v[22:25], v[14:17], v[38:41], v[22:25]
	v_mfma_f32_16x16x32_bf16 v[14:17], v[14:17], v[30:33], v[26:29]
	v_mfma_f32_16x16x32_bf16 v[14:17], v[18:21], v[38:41], v[14:17]
	ds_read_b128 v[18:21], v145 offset:30656
	s_nop 0
	ds_read_b128 v[26:29], v145 offset:65472
	s_waitcnt lgkmcnt(1)
	v_mfma_f32_16x16x32_bf16 v[10:13], v[10:13], v[18:21], v[22:25]
	s_waitcnt lgkmcnt(0)
	v_mfma_f32_16x16x32_bf16 v[10:13], v[2:5], v[26:29], v[10:13]
	v_mfma_f32_16x16x32_bf16 v[2:5], v[2:5], v[18:21], v[14:17]
	v_mfma_f32_16x16x32_bf16 v[2:5], v[6:9], v[26:29], v[2:5]
	v_lshlrev_b64 v[6:7], s10, v[76:77]
	v_lshl_add_u64 v[6:7], s[0:1], 0, v[6:7]
	v_lshlrev_b64 v[6:7], 12, v[6:7]
	v_lshl_add_u64 v[6:7], v[78:79], 0, v[6:7]
	s_nop 1
	v_cvt_pk_bf16_f32 v8, v10, v11
	v_cvt_pk_bf16_f32 v9, v12, v13
	v_cvt_pk_bf16_f32 v2, v2, v3
	v_cvt_pk_bf16_f32 v3, v4, v5
	global_store_dwordx2 v[6:7], v[8:9], off
	global_store_dwordx2 v[6:7], v[2:3], off offset:2048
	s_barrier
	s_cmp_lg_u32 s101, 0
	s_cbranch_scc1 .LBB0_390

; __global__ void __launch_bounds__(NTHR, 2) mega(Params p) {
	.amdhsa_kernel _Z4mega6Params
		.amdhsa_group_segment_fixed_size 0
		.amdhsa_private_segment_fixed_size 0
		.amdhsa_kernarg_size 448
		.amdhsa_user_sgpr_count 2
		.amdhsa_user_sgpr_dispatch_ptr 0
		.amdhsa_user_sgpr_queue_ptr 0
		.amdhsa_user_sgpr_kernarg_segment_ptr 1
		.amdhsa_user_sgpr_dispatch_id 0
		.amdhsa_user_sgpr_kernarg_preload_length 0
		.amdhsa_user_sgpr_kernarg_preload_offset 0
		.amdhsa_user_sgpr_private_segment_size 0
		.amdhsa_uses_dynamic_stack 0
		.amdhsa_enable_private_segment 0
		.amdhsa_system_sgpr_workgroup_id_x 1
		.amdhsa_system_sgpr_workgroup_id_y 0
		.amdhsa_system_sgpr_workgroup_id_z 0
		.amdhsa_system_sgpr_workgroup_info 0
		.amdhsa_system_vgpr_workitem_id 2
		.amdhsa_next_free_vgpr 256
		.amdhsa_next_free_sgpr 102
		.amdhsa_accum_offset 256
		.amdhsa_reserve_vcc 1
		.amdhsa_float_round_mode_32 0
		.amdhsa_float_round_mode_16_64 0
		.amdhsa_float_denorm_mode_32 3
		.amdhsa_float_denorm_mode_16_64 3
		.amdhsa_dx10_clamp 1
		.amdhsa_ieee_mode 1
		.amdhsa_fp16_overflow 0
		.amdhsa_tg_split 0
		.amdhsa_exception_fp_ieee_invalid_op 0
		.amdhsa_exception_fp_denorm_src 0
		.amdhsa_exception_fp_ieee_div_zero 0
		.amdhsa_exception_fp_ieee_overflow 0
		.amdhsa_exception_fp_ieee_underflow 0
		.amdhsa_exception_fp_ieee_inexact 0
		.amdhsa_exception_int_div_zero 0
	.end_amdhsa_kernel

; __global__ void __launch_bounds__(NTHR, 2) mega(Params p) {
amdhsa.kernels:
  - .agpr_count:     0
    .args:
      - .offset:         0
        .size:           192
        .value_kind:     by_value
      - .offset:         192
        .size:           4
        .value_kind:     hidden_block_count_x
      - .offset:         196
        .size:           4
        .value_kind:     hidden_block_count_y
      - .offset:         200
        .size:           4
        .value_kind:     hidden_block_count_z
      - .offset:         204
        .size:           2
        .value_kind:     hidden_group_size_x
      - .offset:         206
        .size:           2
        .value_kind:     hidden_group_size_y
      - .offset:         208
        .size:           2
        .value_kind:     hidden_group_size_z
      - .offset:         210
        .size:           2
        .value_kind:     hidden_remainder_x
      - .offset:         212
        .size:           2
        .value_kind:     hidden_remainder_y
      - .offset:         214
        .size:           2
        .value_kind:     hidden_remainder_z
      - .offset:         232
        .size:           8
        .value_kind:     hidden_global_offset_x
      - .offset:         240
        .size:           8
        .value_kind:     hidden_global_offset_y
      - .offset:         248
        .size:           8
        .value_kind:     hidden_global_offset_z
      - .offset:         256
        .size:           2
        .value_kind:     hidden_grid_dims
      - .offset:         280
        .size:           8
        .value_kind:     hidden_multigrid_sync_arg
      - .offset:         312
        .size:           4
        .value_kind:     hidden_dynamic_lds_size
    .group_segment_fixed_size: 0
    .kernarg_segment_align: 8
    .kernarg_segment_size: 448
    .language:       OpenCL C
    .language_version:
      - 2
      - 0
    .max_flat_workgroup_size: 512
    .name:           _Z4mega6Params
    .private_segment_fixed_size: 0
    .sgpr_count:     108
    .sgpr_spill_count: 244
    .symbol:         _Z4mega6Params.kd
    .uniform_work_group_size: 1
    .uses_dynamic_stack: false
    .vgpr_count:     256
    .vgpr_spill_count: 0
    .wavefront_size: 64
